# phase 0 weight transpose: tile order remapped so concurrent workgroups read neighbouring column blocks of the same rows
# baseline (speedup 1.0000x reference)
; __device__ __forceinline__ TDesc tile_desc(const Params& P, int t) {
;     unsigned char* ws = P.ws; TDesc d; int tl, nkt;
;     if (t < 2304) { tl = t; nkt = 16; const int kt = tl % nkt, nt = tl / nkt; const int n0 = nt * 64; d.ld = 9224; d.ldd = 2048;
;         d.src = P.in[8] + (size_t)kt * 128 * d.ld + n0 + (n0 >= 5120 ? 8 : 0); d.dst = (bf16_t*)(ws + O_WINT) + (size_t)n0 * d.ldd + kt * 128; }
; __device__ __forceinline__ void phase0(const Params& P, unsigned char* shm) {
;     ...
;         int t = blockIdx.x; f32x4 v[4]; TDesc d = tile_desc(P, t < 2304 ? t : 0);
;         if (t < 2304) {
; #pragma unroll
;             for (int i = 0; i < 4; ++i) v[i] = *(const f32x4*)(d.src + (size_t)(r0 + 32 * i) * d.ld + c4 * 4); }
.LBB0_17:
	s_load_dwordx16 s[16:31], s[0:1], 0x80
	s_cmp_lt_i32 s14, 1
	v_lshrrev_b32_e32 v215, 6, v214
	s_waitcnt lgkmcnt(0)
	v_writelane_b32 v245, s16, 18
	s_nop 1
	v_writelane_b32 v245, s17, 19
	v_writelane_b32 v245, s18, 20
	v_writelane_b32 v245, s19, 21
	v_writelane_b32 v245, s20, 22
	v_writelane_b32 v245, s21, 23
	v_writelane_b32 v245, s22, 24
	v_writelane_b32 v245, s23, 25
	v_writelane_b32 v245, s24, 26
	v_writelane_b32 v245, s25, 27
	v_writelane_b32 v245, s26, 28
	v_writelane_b32 v245, s27, 29
	v_writelane_b32 v245, s28, 30
	v_writelane_b32 v245, s29, 31
	v_writelane_b32 v245, s30, 32
	v_writelane_b32 v245, s31, 33
	s_load_dwordx16 s[16:31], s[0:1], 0xc0
	s_cselect_b64 s[0:1], -1, 0
	s_cmp_gt_i32 s15, 0
	s_cselect_b64 s[2:3], -1, 0
	s_and_b64 s[0:1], s[0:1], s[2:3]
	s_waitcnt lgkmcnt(0)
	v_writelane_b32 v245, s16, 34
	s_andn2_b64 vcc, exec, s[0:1]
	s_nop 0
	v_writelane_b32 v245, s17, 35
	v_writelane_b32 v245, s18, 36
	v_writelane_b32 v245, s19, 37
	v_writelane_b32 v245, s20, 38
	v_writelane_b32 v245, s21, 39
	v_writelane_b32 v245, s22, 40
	v_writelane_b32 v245, s23, 41
	v_writelane_b32 v245, s24, 42
	v_writelane_b32 v245, s25, 43
	v_writelane_b32 v245, s26, 44
	v_writelane_b32 v245, s27, 45
	v_writelane_b32 v245, s28, 46
	v_writelane_b32 v245, s29, 47
	v_writelane_b32 v245, s30, 48
	v_writelane_b32 v245, s31, 49
	v_writelane_b32 v245, s88, 50
	s_nop 1
	v_writelane_b32 v245, s89, 51
	s_cbranch_vccnz .LBB0_124
	s_cmpk_gt_i32 s94, 0x8ff
	s_cbranch_scc1 .LBB0_23
	s_add_u32 s6, s12, 0x2100000
	s_addc_u32 s7, s13, 0
	s_mul_hi_u32 s98, s94, 0x1c71c72
	s_mul_i32 s99, s98, 0x90
	s_sub_i32 s99, s94, s99
	s_lshl_b32 s99, s99, 4
	s_add_i32 s100, s99, s98
	s_ashr_i32 s0, s100, 31
	s_lshr_b32 s0, s0, 28
	s_add_i32 s2, s100, s0
	s_and_b32 s0, s2, -16
	s_sub_i32 s4, s100, s0
	s_mul_i32 s0, s4, 0x120400
	s_ashr_i32 s1, s0, 31
	s_lshl_b64 s[0:1], s[0:1], 2
	v_readlane_b32 s16, v245, 2
	v_readlane_b32 s17, v245, 3
	s_add_u32 s5, s16, s0
	s_addc_u32 s8, s17, s1
	s_lshl_b32 s0, s2, 2
	s_andn2_b32 s0, s0, 63
	s_ashr_i32 s1, s0, 31
	s_lshl_b64 s[2:3], s[0:1], 2
	s_add_u32 s2, s5, s2
	s_addc_u32 s3, s8, s3
	s_cmpk_gt_i32 s100, 0x4ff
	s_cselect_b32 s5, 32, 0
	v_and_b32_e32 v17, 15, v214
	v_lshrrev_b32_e32 v19, 4, v214
	s_add_u32 s2, s2, s5
	v_mov_b32_e32 v33, 0
	v_mul_u32_u24_e32 v16, 0x2408, v19
	v_lshlrev_b32_e32 v32, 4, v17
	s_addc_u32 s3, s3, 0
	v_add_u32_e32 v21, 0, v32
	v_lshl_add_u64 v[0:1], s[2:3], 0, v[32:33]
	v_lshlrev_b32_e32 v32, 2, v16
	v_lshl_add_u64 v[8:9], v[0:1], 0, v[32:33]
	s_mov_b32 s2, 0x120000
	v_add_co_u32_e32 v0, vcc, s2, v8
	s_mov_b32 s2, 0x240000
	s_nop 0
	v_addc_co_u32_e32 v1, vcc, 0, v9, vcc
	v_add_co_u32_e32 v10, vcc, s2, v8
	s_mov_b32 s2, 0x360000
	s_nop 0
	v_addc_co_u32_e32 v11, vcc, 0, v9, vcc
	global_load_dwordx4 v[4:7], v[8:9], off
	s_nop 0
	global_load_dwordx4 v[0:3], v[0:1], off offset:1024
	v_add_co_u32_e32 v8, vcc, s2, v8
	s_lshl_b64 s[0:1], s[0:1], 12
	s_nop 0
	v_addc_co_u32_e32 v9, vcc, 0, v9, vcc
	global_load_dwordx4 v[12:15], v[10:11], off offset:2048
	s_nop 0
	global_load_dwordx4 v[8:11], v[8:9], off offset:3072
	s_add_u32 s2, s6, s0
	v_lshlrev_b32_e32 v20, 3, v214
	s_addc_u32 s3, s7, s1
	s_lshl_b32 s0, s4, 7
	v_lshlrev_b32_e32 v18, 2, v17
	v_lshrrev_b32_e32 v17, 3, v214
	v_and_b32_e32 v20, 56, v20
	s_ashr_i32 s1, s0, 31
	v_lshlrev_b32_e32 v23, 2, v17
	v_lshlrev_b32_e32 v22, 11, v17
	v_add_u32_e32 v17, 32, v19
	v_mul_u32_u24_e32 v24, 0x41, v20
	s_lshl_b64 s[0:1], s[0:1], 1
	v_mul_u32_u24_e32 v19, 0x104, v19
	v_lshlrev_b32_e32 v24, 2, v24
	v_mul_u32_u24_e32 v17, 0x104, v17
	s_add_u32 s0, s2, s0
	v_add3_u32 v40, 0, v23, v24
	v_add3_u32 v41, 0, v24, v23
	s_addc_u32 s1, s3, s1
	v_lshlrev_b32_e32 v34, 2, v18
	v_lshlrev_b32_e32 v36, 2, v16
	v_add_u32_e32 v42, v21, v19
	v_add_u32_e32 v43, v21, v17
	v_lshlrev_b32_e32 v32, 1, v22
	v_lshlrev_b32_e32 v38, 1, v20
	s_mov_b32 s8, s94
	v_readlane_b32 s18, v245, 4
	v_readlane_b32 s19, v245, 5
	v_readlane_b32 s20, v245, 6
	v_readlane_b32 s21, v245, 7
	v_readlane_b32 s22, v245, 8
	v_readlane_b32 s23, v245, 9
	v_readlane_b32 s24, v245, 10
	v_readlane_b32 s25, v245, 11
	v_readlane_b32 s26, v245, 12
	v_readlane_b32 s27, v245, 13
	v_readlane_b32 s28, v245, 14
	v_readlane_b32 s29, v245, 15
	v_readlane_b32 s30, v245, 16
	v_readlane_b32 s31, v245, 17
	s_branch .LBB0_21

; __device__ __forceinline__ TDesc tile_desc(const Params& P, int t) {
;     unsigned char* ws = P.ws; TDesc d; int tl, nkt;
;     if (t < 2304) { tl = t; nkt = 16; const int kt = tl % nkt, nt = tl / nkt; const int n0 = nt * 64; d.ld = 9224; d.ldd = 2048;
;         d.src = P.in[8] + (size_t)kt * 128 * d.ld + n0 + (n0 >= 5120 ? 8 : 0); d.dst = (bf16_t*)(ws + O_WINT) + (size_t)n0 * d.ldd + kt * 128; }
; __device__ __forceinline__ void phase0(const Params& P, unsigned char* shm) {
;     ...
;         while (t < 2304) {
;             const int tn = t + gridDim.x; f32x4 vn[4]; TDesc dn = tile_desc(P, tn < 2304 ? tn : 0);
;             if (tn < 2304) {
; #pragma unroll
;                 for (int i = 0; i < 4; ++i) vn[i] = *(const f32x4*)(dn.src + (size_t)(r0 + 32 * i) * dn.ld + c4 * 4); }
.LBB0_21:
	s_add_i32 s8, s8, s96
	s_cmpk_gt_i32 s8, 0x8ff
	s_cselect_b64 s[2:3], -1, 0
	s_cmpk_lt_i32 s8, 0x900
	s_cselect_b32 s4, s8, 0
	s_mul_hi_u32 s98, s4, 0x1c71c72
	s_mul_i32 s99, s98, 0x90
	s_sub_i32 s99, s4, s99
	s_lshl_b32 s99, s99, 4
	s_add_i32 s4, s99, s98
	s_mov_b32 s100, s4
	s_ashr_i32 s5, s4, 31
	s_lshr_b32 s5, s5, 28
	s_add_i32 s5, s4, s5
	s_and_b32 s9, s5, -16
	s_sub_i32 s9, s4, s9
	s_lshl_b32 s4, s5, 2
	s_andn2_b32 s4, s4, 63
	s_ashr_i32 s5, s4, 31
	s_and_b64 vcc, exec, s[2:3]
	s_cbranch_vccnz .LBB0_20
	s_mul_i32 s10, s9, 0x120400
	s_ashr_i32 s11, s10, 31
	s_lshl_b64 s[10:11], s[10:11], 2
	v_readlane_b32 s16, v245, 2
	v_readlane_b32 s17, v245, 3
	s_add_u32 s16, s16, s10
	s_addc_u32 s17, s17, s11
	s_lshl_b64 s[10:11], s[4:5], 2
	s_add_u32 s10, s16, s10
	s_addc_u32 s11, s17, s11
	s_cmpk_gt_i32 s100, 0x4ff
	s_cselect_b32 s16, 32, 0
	s_add_u32 s10, s10, s16
	s_addc_u32 s11, s11, 0
	v_mov_b32_e32 v35, v33
	v_lshl_add_u64 v[16:17], s[10:11], 0, v[34:35]
	v_mov_b32_e32 v37, v33
	v_lshl_add_u64 v[24:25], v[16:17], 0, v[36:37]
	v_add_co_u32_e32 v20, vcc, 0x120000, v24
	v_readlane_b32 s18, v245, 4
	s_nop 0
	v_addc_co_u32_e32 v21, vcc, 0, v25, vcc
	v_add_co_u32_e32 v26, vcc, 0x240000, v24
	global_load_dwordx4 v[16:19], v[24:25], off
	s_nop 0
	global_load_dwordx4 v[20:23], v[20:21], off offset:1024
	v_addc_co_u32_e32 v27, vcc, 0, v25, vcc
	v_add_co_u32_e32 v28, vcc, 0x360000, v24
	v_readlane_b32 s19, v245, 5
	s_nop 0
	v_addc_co_u32_e32 v29, vcc, 0, v25, vcc
	global_load_dwordx4 v[24:27], v[26:27], off offset:2048
	s_nop 0
	global_load_dwordx4 v[28:31], v[28:29], off offset:3072
	v_readlane_b32 s20, v245, 6
	v_readlane_b32 s21, v245, 7
	v_readlane_b32 s22, v245, 8
	v_readlane_b32 s23, v245, 9
	v_readlane_b32 s24, v245, 10
	v_readlane_b32 s25, v245, 11
	v_readlane_b32 s26, v245, 12
	v_readlane_b32 s27, v245, 13
	v_readlane_b32 s28, v245, 14
	v_readlane_b32 s29, v245, 15
	v_readlane_b32 s30, v245, 16
	v_readlane_b32 s31, v245, 17
	s_branch .LBB0_20
